# v23 + P1 K-loop LDS-DMA loads in SGPR-base+32-bit-offset form (no 64-bit VALU address adds in the load segments)
# speedup vs baseline: 1.0032x; 1.0032x over previous
; #define PG8_STAGE(bufoff, gbase, voff) do { _Pragma("unroll") for (int _i = 0; _i < 2; ++_i) \
;         __builtin_amdgcn_global_load_lds((const unsigned*)((const char*)(gbase) + (voff)[_i]), (PG8_LAS unsigned*)(lds + (bufoff) + ldsw + _i * 8192), 16, 0, 0); } while (0)
; #define PG8_LDA(dst, b, h) do { _Pragma("unroll") for (int m = 0; m < 4; ++m) _Pragma("unroll") for (int k = 0; k < 2; ++k) dst[m][k] = *(const PG8_LAS bf16x8*)(lds + PG8_SA(b, h) + aoff + m * 2048 + k * 1024); } while (0)
; #define PG8_LDB(dst, b, h) do { _Pragma("unroll") for (int n = 0; n < 2; ++n) _Pragma("unroll") for (int k = 0; k < 2; ++k) dst[n][k] = *(const PG8_LAS bf16x8*)(lds + PG8_SB(b, h) + boff + n * 2048 + k * 1024); } while (0)
; #define PG8_MMA(ai, bj, At, Bt) do { __builtin_amdgcn_s_setprio(1); _Pragma("unroll") for (int m = 0; m < 4; ++m) _Pragma("unroll") for (int n = 0; n < 2; ++n) _Pragma("unroll") for (int k = 0; k < 2; ++k) \
;         acc[ai][bj][m][n] = __builtin_amdgcn_mfma_f32_16x16x32_bf16(Bt[n][k], At[m][k], acc[ai][bj][m][n], 0, 0, 0); __builtin_amdgcn_s_setprio(0); } while (0)
; #define PG8_WAIT_V(n) asm volatile("s_waitcnt vmcnt(" #n ")" ::: "memory")
; #define PG8_WAIT_L(n) asm volatile("s_waitcnt lgkmcnt(" #n ")" ::: "memory")
; #define PG8_BAR __builtin_amdgcn_s_barrier()
; #define PG8_SCHED __builtin_amdgcn_sched_barrier(0)
; template <class Epi, class Sched, bool ALIGN_EPI = false, bool SP2 = false>
; __device__ __forceinline__ void gemm_phase(PG8_LAS unsigned char* lds, const Gemm g, const Sched& S, const Epi& E) {
;     ...
;             PG8_LDB(B0, 0, 0); PG8_LDB(B1, 0, 1); PG8_SCHED; PG8_LDA(At, 0, 0); PG8_STAGE(PG8_SA(1, 1), a1 + hstep, voffA);
;             PG8_WAIT_V(8); PG8_WAIT_L(0); PG8_BAR; PG8_MMA(0, 0, At, B0); PG8_MMA(0, 1, At, B1); PG8_BAR; PG8_SCHED;
;             PG8_LDA(At, 0, 1); PG8_STAGE(PG8_SB(0, 0), b2, voffB); PG8_STAGE(PG8_SB(0, 1), b2 + hstep, voffB); PG8_STAGE(PG8_SA(0, 0), a2, voffA);
;             PG8_WAIT_V(8); PG8_WAIT_L(0); PG8_BAR; PG8_MMA(1, 0, At, B0); PG8_MMA(1, 1, At, B1); PG8_BAR; PG8_SCHED;
.LBB0_162:
	ds_read_b128 v[130:133], v183
	ds_read_b128 v[134:137], v183 offset:1024
	ds_read_b128 v[138:141], v183 offset:2048
	ds_read_b128 v[142:145], v183 offset:3072
	ds_read_b128 v[172:175], v184
	ds_read_b128 v[176:179], v184 offset:1024
	ds_read_b128 v[192:195], v184 offset:2048
	ds_read_b128 v[196:199], v184 offset:3072
	s_add_u32 s50, s48, 0xfffc0080
	s_addc_u32 s51, s49, -1
	s_cmp_eq_u32 s93, 12
	s_cselect_b32 s65, s5, s51
	s_cselect_b32 s64, s34, s50
	s_cselect_b32 s51, s27, s92
	s_cselect_b32 s50, s35, s41
	s_add_i32 m0, s47, 0xc000
	ds_read_b128 v[200:203], v185
	ds_read_b128 v[204:207], v185 offset:1024
	ds_read_b128 v[208:211], v185 offset:2048
	ds_read_b128 v[212:215], v185 offset:3072
	ds_read_b128 v[216:219], v185 offset:4096
	ds_read_b128 v[220:223], v185 offset:5120
	ds_read_b128 v[224:227], v185 offset:6144
	ds_read_b128 v[228:231], v185 offset:7168
	global_load_lds_dwordx4 v164, s[48:49]
	s_add_i32 m0, s47, 0xe000
	s_nop 0
	global_load_lds_dwordx4 v166, s[48:49]
	s_waitcnt vmcnt(8)
	s_waitcnt lgkmcnt(0)
	s_barrier
	s_setprio 1
	s_waitcnt lgkmcnt(0)
	v_mfma_f32_16x16x32_bf16 v[126:129], v[130:133], v[200:203], v[126:129]
	v_mfma_f32_16x16x32_bf16 v[122:125], v[138:141], v[200:203], v[122:125]
	v_mfma_f32_16x16x32_bf16 v[110:113], v[130:133], v[208:211], v[110:113]
	v_mfma_f32_16x16x32_bf16 v[106:109], v[138:141], v[208:211], v[106:109]
	v_mfma_f32_16x16x32_bf16 v[94:97], v[130:133], v[216:219], v[94:97]
	v_mfma_f32_16x16x32_bf16 v[90:93], v[138:141], v[216:219], v[90:93]
	v_mfma_f32_16x16x32_bf16 v[78:81], v[130:133], v[224:227], v[78:81]
	v_mfma_f32_16x16x32_bf16 v[74:77], v[138:141], v[224:227], v[74:77]
	v_mfma_f32_16x16x32_bf16 v[126:129], v[134:137], v[204:207], v[126:129]
	v_mfma_f32_16x16x32_bf16 v[122:125], v[142:145], v[204:207], v[122:125]
	v_mfma_f32_16x16x32_bf16 v[110:113], v[134:137], v[212:215], v[110:113]
	v_mfma_f32_16x16x32_bf16 v[106:109], v[142:145], v[212:215], v[106:109]
	v_mfma_f32_16x16x32_bf16 v[94:97], v[134:137], v[220:223], v[94:97]
	v_mfma_f32_16x16x32_bf16 v[90:93], v[142:145], v[220:223], v[90:93]
	v_mfma_f32_16x16x32_bf16 v[78:81], v[134:137], v[228:231], v[78:81]
	v_mfma_f32_16x16x32_bf16 v[74:77], v[142:145], v[228:231], v[74:77]
	s_setprio 0
	s_setprio 1
	v_mfma_f32_16x16x32_bf16 v[118:121], v[172:175], v[200:203], v[118:121]
	v_mfma_f32_16x16x32_bf16 v[114:117], v[192:195], v[200:203], v[114:117]
	v_mfma_f32_16x16x32_bf16 v[102:105], v[172:175], v[208:211], v[102:105]
	v_mfma_f32_16x16x32_bf16 v[98:101], v[192:195], v[208:211], v[98:101]
	v_mfma_f32_16x16x32_bf16 v[86:89], v[172:175], v[216:219], v[86:89]
	v_mfma_f32_16x16x32_bf16 v[82:85], v[192:195], v[216:219], v[82:85]
	v_mfma_f32_16x16x32_bf16 v[70:73], v[172:175], v[224:227], v[70:73]
	v_mfma_f32_16x16x32_bf16 v[66:69], v[192:195], v[224:227], v[66:69]
	v_mfma_f32_16x16x32_bf16 v[118:121], v[176:179], v[204:207], v[118:121]
	v_mfma_f32_16x16x32_bf16 v[114:117], v[196:199], v[204:207], v[114:117]
	v_mfma_f32_16x16x32_bf16 v[102:105], v[176:179], v[212:215], v[102:105]
	v_mfma_f32_16x16x32_bf16 v[98:101], v[196:199], v[212:215], v[98:101]
	v_mfma_f32_16x16x32_bf16 v[86:89], v[176:179], v[220:223], v[86:89]
	v_mfma_f32_16x16x32_bf16 v[82:85], v[196:199], v[220:223], v[82:85]
	v_mfma_f32_16x16x32_bf16 v[70:73], v[176:179], v[228:231], v[70:73]
	v_mfma_f32_16x16x32_bf16 v[66:69], v[196:199], v[228:231], v[66:69]
	s_setprio 0
	s_barrier
	s_add_i32 s94, s85, s72
	s_mov_b32 m0, s94
	ds_read_b128 v[200:203], v185 offset:16384
	ds_read_b128 v[204:207], v185 offset:17408
	ds_read_b128 v[208:211], v185 offset:18432
	ds_read_b128 v[212:215], v185 offset:19456
	ds_read_b128 v[216:219], v185 offset:20480
	ds_read_b128 v[220:223], v185 offset:21504
	ds_read_b128 v[224:227], v185 offset:22528
	ds_read_b128 v[228:231], v185 offset:23552
	global_load_lds_dwordx4 v148, s[50:51]
	s_add_i32 m0, s94, 0x2000
	s_add_u32 s94, s50, 0x40000
	s_addc_u32 s95, s51, 0
	s_add_i32 s96, s86, s72
	global_load_lds_dwordx4 v152, s[50:51]
	s_mov_b32 m0, s96
	s_nop 0
	global_load_lds_dwordx4 v148, s[94:95]
	s_add_i32 m0, s96, 0x2000
	s_nop 0
	global_load_lds_dwordx4 v152, s[94:95]
	s_mov_b32 m0, s47
	s_nop 0
	global_load_lds_dwordx4 v146, s[64:65]
	s_mov_b32 m0, s73
	s_nop 0
	global_load_lds_dwordx4 v150, s[64:65]
	s_waitcnt vmcnt(8)
	s_waitcnt lgkmcnt(0)
	s_barrier
	s_setprio 1
	s_waitcnt lgkmcnt(0)
	v_mfma_f32_16x16x32_bf16 v[62:65], v[130:133], v[200:203], v[62:65]
	v_mfma_f32_16x16x32_bf16 v[58:61], v[138:141], v[200:203], v[58:61]
	v_mfma_f32_16x16x32_bf16 v[46:49], v[130:133], v[208:211], v[46:49]
	v_mfma_f32_16x16x32_bf16 v[42:45], v[138:141], v[208:211], v[42:45]
	v_mfma_f32_16x16x32_bf16 v[30:33], v[130:133], v[216:219], v[30:33]
	v_mfma_f32_16x16x32_bf16 v[26:29], v[138:141], v[216:219], v[26:29]
	v_mfma_f32_16x16x32_bf16 v[14:17], v[130:133], v[224:227], v[14:17]
	v_mfma_f32_16x16x32_bf16 v[10:13], v[138:141], v[224:227], v[10:13]
	v_mfma_f32_16x16x32_bf16 v[62:65], v[134:137], v[204:207], v[62:65]
	v_mfma_f32_16x16x32_bf16 v[58:61], v[142:145], v[204:207], v[58:61]
	v_mfma_f32_16x16x32_bf16 v[46:49], v[134:137], v[212:215], v[46:49]
	v_mfma_f32_16x16x32_bf16 v[42:45], v[142:145], v[212:215], v[42:45]
	v_mfma_f32_16x16x32_bf16 v[30:33], v[134:137], v[220:223], v[30:33]
	v_mfma_f32_16x16x32_bf16 v[26:29], v[142:145], v[220:223], v[26:29]
	v_mfma_f32_16x16x32_bf16 v[14:17], v[134:137], v[228:231], v[14:17]
	v_mfma_f32_16x16x32_bf16 v[10:13], v[142:145], v[228:231], v[10:13]
	s_setprio 0
	s_setprio 1
	v_mfma_f32_16x16x32_bf16 v[54:57], v[172:175], v[200:203], v[54:57]
	v_mfma_f32_16x16x32_bf16 v[50:53], v[192:195], v[200:203], v[50:53]
	v_mfma_f32_16x16x32_bf16 v[38:41], v[172:175], v[208:211], v[38:41]
	v_mfma_f32_16x16x32_bf16 v[34:37], v[192:195], v[208:211], v[34:37]
	v_mfma_f32_16x16x32_bf16 v[22:25], v[172:175], v[216:219], v[22:25]
	v_mfma_f32_16x16x32_bf16 v[18:21], v[192:195], v[216:219], v[18:21]
	v_mfma_f32_16x16x32_bf16 v[6:9], v[172:175], v[224:227], v[6:9]
	v_mfma_f32_16x16x32_bf16 v[2:5], v[192:195], v[224:227], v[2:5]
	v_mfma_f32_16x16x32_bf16 v[54:57], v[176:179], v[204:207], v[54:57]
	v_mfma_f32_16x16x32_bf16 v[50:53], v[196:199], v[204:207], v[50:53]
	v_mfma_f32_16x16x32_bf16 v[38:41], v[176:179], v[212:215], v[38:41]
	v_mfma_f32_16x16x32_bf16 v[34:37], v[196:199], v[212:215], v[34:37]
	v_mfma_f32_16x16x32_bf16 v[22:25], v[176:179], v[220:223], v[22:25]
	v_mfma_f32_16x16x32_bf16 v[18:21], v[196:199], v[220:223], v[18:21]
	v_mfma_f32_16x16x32_bf16 v[6:9], v[176:179], v[228:231], v[6:9]
	v_mfma_f32_16x16x32_bf16 v[2:5], v[196:199], v[228:231], v[2:5]
	s_setprio 0
	s_barrier
; #define PG8_STAGE(bufoff, gbase, voff) do { _Pragma("unroll") for (int _i = 0; _i < 2; ++_i) \
;         __builtin_amdgcn_global_load_lds((const unsigned*)((const char*)(gbase) + (voff)[_i]), (PG8_LAS unsigned*)(lds + (bufoff) + ldsw + _i * 8192), 16, 0, 0); } while (0)
; #define PG8_LDA(dst, b, h) do { _Pragma("unroll") for (int m = 0; m < 4; ++m) _Pragma("unroll") for (int k = 0; k < 2; ++k) dst[m][k] = *(const PG8_LAS bf16x8*)(lds + PG8_SA(b, h) + aoff + m * 2048 + k * 1024); } while (0)
; #define PG8_LDB(dst, b, h) do { _Pragma("unroll") for (int n = 0; n < 2; ++n) _Pragma("unroll") for (int k = 0; k < 2; ++k) dst[n][k] = *(const PG8_LAS bf16x8*)(lds + PG8_SB(b, h) + boff + n * 2048 + k * 1024); } while (0)
; #define PG8_MMA(ai, bj, At, Bt) do { __builtin_amdgcn_s_setprio(1); _Pragma("unroll") for (int m = 0; m < 4; ++m) _Pragma("unroll") for (int n = 0; n < 2; ++n) _Pragma("unroll") for (int k = 0; k < 2; ++k) \
;         acc[ai][bj][m][n] = __builtin_amdgcn_mfma_f32_16x16x32_bf16(Bt[n][k], At[m][k], acc[ai][bj][m][n], 0, 0, 0); __builtin_amdgcn_s_setprio(0); } while (0)
; #define PG8_WAIT_V(n) asm volatile("s_waitcnt vmcnt(" #n ")" ::: "memory")
; #define PG8_WAIT_L(n) asm volatile("s_waitcnt lgkmcnt(" #n ")" ::: "memory")
; #define PG8_BAR __builtin_amdgcn_s_barrier()
; #define PG8_SCHED __builtin_amdgcn_sched_barrier(0)
; template <class Epi, class Sched, bool ALIGN_EPI = false, bool SP2 = false>
; __device__ __forceinline__ void gemm_phase(PG8_LAS unsigned char* lds, const Gemm g, const Sched& S, const Epi& E) {
;     ...
;             PG8_LDB(B0, 1, 0); PG8_LDB(B1, 1, 1); PG8_SCHED; PG8_LDA(At, 1, 0); PG8_STAGE(PG8_SA(0, 1), a2 + hstep, voffA);
;             PG8_WAIT_V(8); PG8_WAIT_L(0); PG8_BAR; PG8_MMA(0, 0, At, B0); PG8_MMA(0, 1, At, B1); PG8_BAR; PG8_SCHED;
;             PG8_LDA(At, 1, 1); PG8_STAGE(PG8_SB(1, 0), b3, voffB); PG8_STAGE(PG8_SB(1, 1), b3 + hstep, voffB); PG8_STAGE(PG8_SA(1, 0), a3, voffA);
;             PG8_WAIT_V(8); PG8_WAIT_L(0); PG8_BAR; PG8_MMA(1, 0, At, B0); PG8_MMA(1, 1, At, B1); PG8_BAR; PG8_SCHED;
	s_add_i32 s94, 0, 0x18000
	s_add_i32 s95, 0, 0x1c000
	v_add_u32_e32 v142, s94, v181
	v_add_u32_e32 v154, s95, v181
	ds_read_b128 v[130:133], v142
	ds_read_b128 v[134:137], v142 offset:1024
	ds_read_b128 v[138:141], v142 offset:2048
	ds_read_b128 v[142:145], v142 offset:3072
	ds_read_b128 v[172:175], v154
	ds_read_b128 v[176:179], v154 offset:1024
	ds_read_b128 v[192:195], v154 offset:2048
	ds_read_b128 v[196:199], v154 offset:3072
	s_add_u32 s64, s64, 0x40000
	s_addc_u32 s65, s65, 0
	s_mov_b32 m0, s74
	ds_read_b128 v[200:203], v185 offset:32768
	ds_read_b128 v[204:207], v185 offset:33792
	ds_read_b128 v[208:211], v185 offset:34816
	ds_read_b128 v[212:215], v185 offset:35840
	ds_read_b128 v[216:219], v185 offset:36864
	ds_read_b128 v[220:223], v185 offset:37888
	ds_read_b128 v[224:227], v185 offset:38912
	ds_read_b128 v[228:231], v185 offset:39936
	global_load_lds_dwordx4 v146, s[64:65]
	s_mov_b32 m0, s75
	s_nop 0
	global_load_lds_dwordx4 v150, s[64:65]
	s_waitcnt vmcnt(8)
	s_waitcnt lgkmcnt(0)
	s_barrier
	s_setprio 1
	s_waitcnt lgkmcnt(0)
	v_mfma_f32_16x16x32_bf16 v[126:129], v[130:133], v[200:203], v[126:129]
	v_mfma_f32_16x16x32_bf16 v[122:125], v[138:141], v[200:203], v[122:125]
	v_mfma_f32_16x16x32_bf16 v[110:113], v[130:133], v[208:211], v[110:113]
	v_mfma_f32_16x16x32_bf16 v[106:109], v[138:141], v[208:211], v[106:109]
	v_mfma_f32_16x16x32_bf16 v[94:97], v[130:133], v[216:219], v[94:97]
	v_mfma_f32_16x16x32_bf16 v[90:93], v[138:141], v[216:219], v[90:93]
	v_mfma_f32_16x16x32_bf16 v[78:81], v[130:133], v[224:227], v[78:81]
	v_mfma_f32_16x16x32_bf16 v[74:77], v[138:141], v[224:227], v[74:77]
	v_mfma_f32_16x16x32_bf16 v[126:129], v[134:137], v[204:207], v[126:129]
	v_mfma_f32_16x16x32_bf16 v[122:125], v[142:145], v[204:207], v[122:125]
	v_mfma_f32_16x16x32_bf16 v[110:113], v[134:137], v[212:215], v[110:113]
	v_mfma_f32_16x16x32_bf16 v[106:109], v[142:145], v[212:215], v[106:109]
	v_mfma_f32_16x16x32_bf16 v[94:97], v[134:137], v[220:223], v[94:97]
	v_mfma_f32_16x16x32_bf16 v[90:93], v[142:145], v[220:223], v[90:93]
	v_mfma_f32_16x16x32_bf16 v[78:81], v[134:137], v[228:231], v[78:81]
	v_mfma_f32_16x16x32_bf16 v[74:77], v[142:145], v[228:231], v[74:77]
	s_setprio 0
	s_setprio 1
	v_mfma_f32_16x16x32_bf16 v[118:121], v[172:175], v[200:203], v[118:121]
	v_mfma_f32_16x16x32_bf16 v[114:117], v[192:195], v[200:203], v[114:117]
	v_mfma_f32_16x16x32_bf16 v[102:105], v[172:175], v[208:211], v[102:105]
	v_mfma_f32_16x16x32_bf16 v[98:101], v[192:195], v[208:211], v[98:101]
	v_mfma_f32_16x16x32_bf16 v[86:89], v[172:175], v[216:219], v[86:89]
	v_mfma_f32_16x16x32_bf16 v[82:85], v[192:195], v[216:219], v[82:85]
	v_mfma_f32_16x16x32_bf16 v[70:73], v[172:175], v[224:227], v[70:73]
	v_mfma_f32_16x16x32_bf16 v[66:69], v[192:195], v[224:227], v[66:69]
	v_mfma_f32_16x16x32_bf16 v[118:121], v[176:179], v[204:207], v[118:121]
	v_mfma_f32_16x16x32_bf16 v[114:117], v[196:199], v[204:207], v[114:117]
	v_mfma_f32_16x16x32_bf16 v[102:105], v[176:179], v[212:215], v[102:105]
	v_mfma_f32_16x16x32_bf16 v[98:101], v[196:199], v[212:215], v[98:101]
	v_mfma_f32_16x16x32_bf16 v[86:89], v[176:179], v[220:223], v[86:89]
	v_mfma_f32_16x16x32_bf16 v[82:85], v[196:199], v[220:223], v[82:85]
	v_mfma_f32_16x16x32_bf16 v[70:73], v[176:179], v[228:231], v[70:73]
	v_mfma_f32_16x16x32_bf16 v[66:69], v[196:199], v[228:231], v[66:69]
	s_setprio 0
	s_barrier
	s_add_i32 s96, s94, s72
	s_add_u32 s12, s50, 0x80
	s_addc_u32 s13, s51, 0
	s_mov_b32 m0, s96
	ds_read_b128 v[200:203], v185 offset:49152
	ds_read_b128 v[204:207], v185 offset:50176
	ds_read_b128 v[208:211], v185 offset:51200
	ds_read_b128 v[212:215], v185 offset:52224
	ds_read_b128 v[216:219], v185 offset:53248
	ds_read_b128 v[220:223], v185 offset:54272
	ds_read_b128 v[224:227], v185 offset:55296
	ds_read_b128 v[228:231], v185 offset:56320
	global_load_lds_dwordx4 v148, s[12:13]
	s_add_i32 m0, s96, 0x2000
	s_add_u32 s50, s50, 0x40080
	s_addc_u32 s51, s51, 0
	s_add_i32 s96, s95, s72
	global_load_lds_dwordx4 v152, s[12:13]
	s_mov_b32 m0, s96
	s_nop 0
	global_load_lds_dwordx4 v148, s[50:51]
	s_add_i32 m0, s96, 0x2000
	s_nop 0
	global_load_lds_dwordx4 v152, s[50:51]
	s_add_u32 s64, s64, 0xfffc0080
	s_addc_u32 s65, s65, -1
	s_mov_b32 m0, s82
	s_nop 0
	global_load_lds_dwordx4 v146, s[64:65]
	s_mov_b32 m0, s83
	s_nop 0
	global_load_lds_dwordx4 v150, s[64:65]
	s_waitcnt vmcnt(8)
	s_waitcnt lgkmcnt(0)
	s_barrier
	s_setprio 1
	s_waitcnt lgkmcnt(0)
	v_mfma_f32_16x16x32_bf16 v[62:65], v[130:133], v[200:203], v[62:65]
	v_mfma_f32_16x16x32_bf16 v[58:61], v[138:141], v[200:203], v[58:61]
	v_mfma_f32_16x16x32_bf16 v[46:49], v[130:133], v[208:211], v[46:49]
	v_mfma_f32_16x16x32_bf16 v[42:45], v[138:141], v[208:211], v[42:45]
	v_mfma_f32_16x16x32_bf16 v[30:33], v[130:133], v[216:219], v[30:33]
	v_mfma_f32_16x16x32_bf16 v[26:29], v[138:141], v[216:219], v[26:29]
	v_mfma_f32_16x16x32_bf16 v[14:17], v[130:133], v[224:227], v[14:17]
	v_mfma_f32_16x16x32_bf16 v[10:13], v[138:141], v[224:227], v[10:13]
	v_mfma_f32_16x16x32_bf16 v[62:65], v[134:137], v[204:207], v[62:65]
	v_mfma_f32_16x16x32_bf16 v[58:61], v[142:145], v[204:207], v[58:61]
	v_mfma_f32_16x16x32_bf16 v[46:49], v[134:137], v[212:215], v[46:49]
	v_mfma_f32_16x16x32_bf16 v[42:45], v[142:145], v[212:215], v[42:45]
	v_mfma_f32_16x16x32_bf16 v[30:33], v[134:137], v[220:223], v[30:33]
	v_mfma_f32_16x16x32_bf16 v[26:29], v[142:145], v[220:223], v[26:29]
	v_mfma_f32_16x16x32_bf16 v[14:17], v[134:137], v[228:231], v[14:17]
	v_mfma_f32_16x16x32_bf16 v[10:13], v[142:145], v[228:231], v[10:13]
	s_setprio 0
	s_setprio 1
	v_mfma_f32_16x16x32_bf16 v[54:57], v[172:175], v[200:203], v[54:57]
	v_mfma_f32_16x16x32_bf16 v[50:53], v[192:195], v[200:203], v[50:53]
	v_mfma_f32_16x16x32_bf16 v[38:41], v[172:175], v[208:211], v[38:41]
	v_mfma_f32_16x16x32_bf16 v[34:37], v[192:195], v[208:211], v[34:37]
	v_mfma_f32_16x16x32_bf16 v[22:25], v[172:175], v[216:219], v[22:25]
	v_mfma_f32_16x16x32_bf16 v[18:21], v[192:195], v[216:219], v[18:21]
	v_mfma_f32_16x16x32_bf16 v[6:9], v[172:175], v[224:227], v[6:9]
	v_mfma_f32_16x16x32_bf16 v[2:5], v[192:195], v[224:227], v[2:5]
	v_mfma_f32_16x16x32_bf16 v[54:57], v[176:179], v[204:207], v[54:57]
	v_mfma_f32_16x16x32_bf16 v[50:53], v[196:199], v[204:207], v[50:53]
	v_mfma_f32_16x16x32_bf16 v[38:41], v[176:179], v[212:215], v[38:41]
	v_mfma_f32_16x16x32_bf16 v[34:37], v[196:199], v[212:215], v[34:37]
	v_mfma_f32_16x16x32_bf16 v[22:25], v[176:179], v[220:223], v[22:25]
	v_mfma_f32_16x16x32_bf16 v[18:21], v[196:199], v[220:223], v[18:21]
	v_mfma_f32_16x16x32_bf16 v[6:9], v[176:179], v[228:231], v[6:9]
	v_mfma_f32_16x16x32_bf16 v[2:5], v[196:199], v[228:231], v[2:5]
	s_setprio 0
	s_add_i32 s93, s93, 2
	s_add_u32 s48, s48, 0x100
	s_addc_u32 s49, s49, 0
	s_add_u32 s41, s41, 0x100
	s_addc_u32 s92, s92, 0
	s_cmp_gt_u32 s93, 13
	s_cbranch_scc1 .Lp1_kexit
	s_barrier
	s_branch .LBB0_162

; #define PG8_STAGE(bufoff, gbase, voff) do { _Pragma("unroll") for (int _i = 0; _i < 2; ++_i) \
;         __builtin_amdgcn_global_load_lds((const unsigned*)((const char*)(gbase) + (voff)[_i]), (PG8_LAS unsigned*)(lds + (bufoff) + ldsw + _i * 8192), 16, 0, 0); } while (0)
; #define PG8_LDA(dst, b, h) do { _Pragma("unroll") for (int m = 0; m < 4; ++m) _Pragma("unroll") for (int k = 0; k < 2; ++k) dst[m][k] = *(const PG8_LAS bf16x8*)(lds + PG8_SA(b, h) + aoff + m * 2048 + k * 1024); } while (0)
; #define PG8_LDB(dst, b, h) do { _Pragma("unroll") for (int n = 0; n < 2; ++n) _Pragma("unroll") for (int k = 0; k < 2; ++k) dst[n][k] = *(const PG8_LAS bf16x8*)(lds + PG8_SB(b, h) + boff + n * 2048 + k * 1024); } while (0)
; #define PG8_SCHED __builtin_amdgcn_sched_barrier(0)
; template <class Epi, class Sched, bool ALIGN_EPI = false, bool SP2 = false>
; __device__ __forceinline__ void gemm_phase(PG8_LAS unsigned char* lds, const Gemm g, const Sched& S, const Epi& E) {
;     ...
;             const char* a2 = last ? nA : cA + (size_t)(t + 2) * kstep; const char* b2 = last ? nB : cB + (size_t)(t + 2) * kstep;
;             const char* a3 = a2 + kstep; const char* b3 = b2 + kstep;
;             if (last && has_next) S.a_ready(nxt);
;             if constexpr (SP2) {
;             PG8_LDB(B0, 0, 0); PG8_LDB(B1, 0, 1); PG8_SCHED; PG8_LDA(At, 0, 0); PG8_STAGE(PG8_SA(1, 1), a1 + hstep, voffA);
;     __device__ __forceinline__ void operator()(const f32x4 (&acc)[2][2][4][2], const pg8::Unit& u, int wr, int wc, int fr, int fq) const {
;         const int sec = u.pn >> 1, half = u.pn & 1;
;         bf16_t* base = proj + (size_t)sec * SEC_STRIDE;
;         const int row0 = u.pm * 256 + wr * 64 + fr;
;         if (sec <= 1) {
.LBB0_165:
	s_add_u32 s94, s34, 0x40080
	s_addc_u32 s95, s5, 0
	s_add_i32 m0, s47, 0xc000
	s_nop 0
	global_load_lds_dwordx4 v164, s[94:95]
	s_add_i32 m0, s47, 0xe000
	s_nop 0
	global_load_lds_dwordx4 v166, s[94:95]
	s_ashr_i32 s41, s46, 1
	s_and_b32 s27, s46, 1
	s_mul_i32 s34, s41, 0x5000000
	s_mul_hi_i32 s5, s41, 0x5000000
	s_add_u32 s48, s78, s34
	s_addc_u32 s49, s79, s5
	v_lshl_add_u32 v172, s4, 8, v1
	s_cmp_gt_i32 s41, 1
	s_mov_b64 s[4:5], -1
	s_cbranch_scc1 .LBB0_168
	s_andn2_b64 vcc, exec, s[4:5]
	s_cbranch_vccz .LBB0_205

; #define PG8_STAGE(bufoff, gbase, voff) do { _Pragma("unroll") for (int _i = 0; _i < 2; ++_i) \
;         __builtin_amdgcn_global_load_lds((const unsigned*)((const char*)(gbase) + (voff)[_i]), (PG8_LAS unsigned*)(lds + (bufoff) + ldsw + _i * 8192), 16, 0, 0); } while (0)
; #define PG8_LDA(dst, b, h) do { _Pragma("unroll") for (int m = 0; m < 4; ++m) _Pragma("unroll") for (int k = 0; k < 2; ++k) dst[m][k] = *(const PG8_LAS bf16x8*)(lds + PG8_SA(b, h) + aoff + m * 2048 + k * 1024); } while (0)
; #define PG8_LDB(dst, b, h) do { _Pragma("unroll") for (int n = 0; n < 2; ++n) _Pragma("unroll") for (int k = 0; k < 2; ++k) dst[n][k] = *(const PG8_LAS bf16x8*)(lds + PG8_SB(b, h) + boff + n * 2048 + k * 1024); } while (0)
; #define PG8_MMA(ai, bj, At, Bt) do { __builtin_amdgcn_s_setprio(1); _Pragma("unroll") for (int m = 0; m < 4; ++m) _Pragma("unroll") for (int n = 0; n < 2; ++n) _Pragma("unroll") for (int k = 0; k < 2; ++k) \
;         acc[ai][bj][m][n] = __builtin_amdgcn_mfma_f32_16x16x32_bf16(Bt[n][k], At[m][k], acc[ai][bj][m][n], 0, 0, 0); __builtin_amdgcn_s_setprio(0); } while (0)
; #define PG8_WAIT_V(n) asm volatile("s_waitcnt vmcnt(" #n ")" ::: "memory")
; #define PG8_WAIT_L(n) asm volatile("s_waitcnt lgkmcnt(" #n ")" ::: "memory")
; #define PG8_BAR __builtin_amdgcn_s_barrier()
; #define PG8_SCHED __builtin_amdgcn_sched_barrier(0)
; template <class Epi, class Sched, bool ALIGN_EPI = false, bool SP2 = false>
; __device__ __forceinline__ void gemm_phase(PG8_LAS unsigned char* lds, const Gemm g, const Sched& S, const Epi& E) {
;     ...
;             PG8_LDB(B0, 0, 0); PG8_LDB(B1, 0, 1); PG8_SCHED; PG8_LDA(At, 0, 0); PG8_STAGE(PG8_SA(1, 1), a1 + hstep, voffA);
;             PG8_WAIT_V(8); PG8_WAIT_L(0); PG8_BAR; PG8_MMA(0, 0, At, B0); PG8_MMA(0, 1, At, B1); PG8_BAR; PG8_SCHED;
;             PG8_LDA(At, 0, 1); PG8_STAGE(PG8_SB(0, 0), b2, voffB); PG8_STAGE(PG8_SB(0, 1), b2 + hstep, voffB); PG8_STAGE(PG8_SA(0, 0), a2, voffA);
;             PG8_WAIT_V(8); PG8_WAIT_L(0); PG8_BAR; PG8_MMA(1, 0, At, B0); PG8_MMA(1, 1, At, B1); PG8_BAR; PG8_SCHED;
.Lp1_peel:
	ds_read_b128 v[130:133], v183
	ds_read_b128 v[134:137], v183 offset:1024
	ds_read_b128 v[138:141], v183 offset:2048
	ds_read_b128 v[142:145], v183 offset:3072
	ds_read_b128 v[172:175], v184
	ds_read_b128 v[176:179], v184 offset:1024
	ds_read_b128 v[192:195], v184 offset:2048
	ds_read_b128 v[196:199], v184 offset:3072
	s_add_u32 s50, s48, 0xfffc0080
	s_addc_u32 s51, s49, -1
	s_cmp_eq_u32 s93, 12
	s_cselect_b32 s65, s5, s51
	s_cselect_b32 s64, s34, s50
	s_cselect_b32 s51, s27, s92
	s_cselect_b32 s50, s35, s41
	ds_read_b128 v[200:203], v185
	ds_read_b128 v[204:207], v185 offset:1024
	ds_read_b128 v[208:211], v185 offset:2048
	ds_read_b128 v[212:215], v185 offset:3072
	ds_read_b128 v[216:219], v185 offset:4096
	ds_read_b128 v[220:223], v185 offset:5120
	ds_read_b128 v[224:227], v185 offset:6144
	ds_read_b128 v[228:231], v185 offset:7168
	s_waitcnt vmcnt(24)
	s_waitcnt lgkmcnt(0)
	s_barrier
	s_setprio 1
	s_waitcnt lgkmcnt(0)
	v_mfma_f32_16x16x32_bf16 v[126:129], v[130:133], v[200:203], 0
	v_mfma_f32_16x16x32_bf16 v[122:125], v[138:141], v[200:203], 0
	v_mfma_f32_16x16x32_bf16 v[110:113], v[130:133], v[208:211], 0
	v_mfma_f32_16x16x32_bf16 v[106:109], v[138:141], v[208:211], 0
	v_mfma_f32_16x16x32_bf16 v[94:97], v[130:133], v[216:219], 0
	v_mfma_f32_16x16x32_bf16 v[90:93], v[138:141], v[216:219], 0
	v_mfma_f32_16x16x32_bf16 v[78:81], v[130:133], v[224:227], 0
	v_mfma_f32_16x16x32_bf16 v[74:77], v[138:141], v[224:227], 0
	v_mfma_f32_16x16x32_bf16 v[126:129], v[134:137], v[204:207], v[126:129]
	v_mfma_f32_16x16x32_bf16 v[122:125], v[142:145], v[204:207], v[122:125]
	v_mfma_f32_16x16x32_bf16 v[110:113], v[134:137], v[212:215], v[110:113]
	v_mfma_f32_16x16x32_bf16 v[106:109], v[142:145], v[212:215], v[106:109]
	v_mfma_f32_16x16x32_bf16 v[94:97], v[134:137], v[220:223], v[94:97]
	v_mfma_f32_16x16x32_bf16 v[90:93], v[142:145], v[220:223], v[90:93]
	v_mfma_f32_16x16x32_bf16 v[78:81], v[134:137], v[228:231], v[78:81]
	v_mfma_f32_16x16x32_bf16 v[74:77], v[142:145], v[228:231], v[74:77]
	s_setprio 0
	s_setprio 1
	v_mfma_f32_16x16x32_bf16 v[118:121], v[172:175], v[200:203], 0
	v_mfma_f32_16x16x32_bf16 v[114:117], v[192:195], v[200:203], 0
	v_mfma_f32_16x16x32_bf16 v[102:105], v[172:175], v[208:211], 0
	v_mfma_f32_16x16x32_bf16 v[98:101], v[192:195], v[208:211], 0
	v_mfma_f32_16x16x32_bf16 v[86:89], v[172:175], v[216:219], 0
	v_mfma_f32_16x16x32_bf16 v[82:85], v[192:195], v[216:219], 0
	v_mfma_f32_16x16x32_bf16 v[70:73], v[172:175], v[224:227], 0
	v_mfma_f32_16x16x32_bf16 v[66:69], v[192:195], v[224:227], 0
	v_mfma_f32_16x16x32_bf16 v[118:121], v[176:179], v[204:207], v[118:121]
	v_mfma_f32_16x16x32_bf16 v[114:117], v[196:199], v[204:207], v[114:117]
	v_mfma_f32_16x16x32_bf16 v[102:105], v[176:179], v[212:215], v[102:105]
	v_mfma_f32_16x16x32_bf16 v[98:101], v[196:199], v[212:215], v[98:101]
	v_mfma_f32_16x16x32_bf16 v[86:89], v[176:179], v[220:223], v[86:89]
	v_mfma_f32_16x16x32_bf16 v[82:85], v[196:199], v[220:223], v[82:85]
	v_mfma_f32_16x16x32_bf16 v[70:73], v[176:179], v[228:231], v[70:73]
	v_mfma_f32_16x16x32_bf16 v[66:69], v[196:199], v[228:231], v[66:69]
	s_setprio 0
	s_barrier
	s_add_i32 s94, s85, s72
	s_mov_b32 m0, s94
	ds_read_b128 v[200:203], v185 offset:16384
	ds_read_b128 v[204:207], v185 offset:17408
	ds_read_b128 v[208:211], v185 offset:18432
	ds_read_b128 v[212:215], v185 offset:19456
	ds_read_b128 v[216:219], v185 offset:20480
	ds_read_b128 v[220:223], v185 offset:21504
	ds_read_b128 v[224:227], v185 offset:22528
	ds_read_b128 v[228:231], v185 offset:23552
	global_load_lds_dwordx4 v148, s[50:51]
	s_add_i32 m0, s94, 0x2000
	s_add_u32 s94, s50, 0x40000
	s_addc_u32 s95, s51, 0
	s_add_i32 s96, s86, s72
	global_load_lds_dwordx4 v152, s[50:51]
	s_mov_b32 m0, s96
	s_nop 0
	global_load_lds_dwordx4 v148, s[94:95]
	s_add_i32 m0, s96, 0x2000
	s_nop 0
	global_load_lds_dwordx4 v152, s[94:95]
	s_mov_b32 m0, s47
	s_nop 0
	global_load_lds_dwordx4 v146, s[64:65]
	s_mov_b32 m0, s73
	s_nop 0
	global_load_lds_dwordx4 v150, s[64:65]
	s_waitcnt vmcnt(24)
	s_waitcnt lgkmcnt(0)
	s_barrier
	s_setprio 1
	s_waitcnt lgkmcnt(0)
	v_mfma_f32_16x16x32_bf16 v[62:65], v[130:133], v[200:203], 0
	v_mfma_f32_16x16x32_bf16 v[58:61], v[138:141], v[200:203], 0
	v_mfma_f32_16x16x32_bf16 v[46:49], v[130:133], v[208:211], 0
	v_mfma_f32_16x16x32_bf16 v[42:45], v[138:141], v[208:211], 0
	v_mfma_f32_16x16x32_bf16 v[30:33], v[130:133], v[216:219], 0
	v_mfma_f32_16x16x32_bf16 v[26:29], v[138:141], v[216:219], 0
	v_mfma_f32_16x16x32_bf16 v[14:17], v[130:133], v[224:227], 0
	v_mfma_f32_16x16x32_bf16 v[10:13], v[138:141], v[224:227], 0
	v_mfma_f32_16x16x32_bf16 v[62:65], v[134:137], v[204:207], v[62:65]
	v_mfma_f32_16x16x32_bf16 v[58:61], v[142:145], v[204:207], v[58:61]
	v_mfma_f32_16x16x32_bf16 v[46:49], v[134:137], v[212:215], v[46:49]
	v_mfma_f32_16x16x32_bf16 v[42:45], v[142:145], v[212:215], v[42:45]
	v_mfma_f32_16x16x32_bf16 v[30:33], v[134:137], v[220:223], v[30:33]
	v_mfma_f32_16x16x32_bf16 v[26:29], v[142:145], v[220:223], v[26:29]
	v_mfma_f32_16x16x32_bf16 v[14:17], v[134:137], v[228:231], v[14:17]
	v_mfma_f32_16x16x32_bf16 v[10:13], v[142:145], v[228:231], v[10:13]
	s_setprio 0
	s_setprio 1
	v_mfma_f32_16x16x32_bf16 v[54:57], v[172:175], v[200:203], 0
	v_mfma_f32_16x16x32_bf16 v[50:53], v[192:195], v[200:203], 0
	v_mfma_f32_16x16x32_bf16 v[38:41], v[172:175], v[208:211], 0
	v_mfma_f32_16x16x32_bf16 v[34:37], v[192:195], v[208:211], 0
	v_mfma_f32_16x16x32_bf16 v[22:25], v[172:175], v[216:219], 0
	v_mfma_f32_16x16x32_bf16 v[18:21], v[192:195], v[216:219], 0
	v_mfma_f32_16x16x32_bf16 v[6:9], v[172:175], v[224:227], 0
	v_mfma_f32_16x16x32_bf16 v[2:5], v[192:195], v[224:227], 0
	v_mfma_f32_16x16x32_bf16 v[54:57], v[176:179], v[204:207], v[54:57]
	v_mfma_f32_16x16x32_bf16 v[50:53], v[196:199], v[204:207], v[50:53]
	v_mfma_f32_16x16x32_bf16 v[38:41], v[176:179], v[212:215], v[38:41]
	v_mfma_f32_16x16x32_bf16 v[34:37], v[196:199], v[212:215], v[34:37]
	v_mfma_f32_16x16x32_bf16 v[22:25], v[176:179], v[220:223], v[22:25]
	v_mfma_f32_16x16x32_bf16 v[18:21], v[196:199], v[220:223], v[18:21]
	v_mfma_f32_16x16x32_bf16 v[6:9], v[176:179], v[228:231], v[6:9]
	v_mfma_f32_16x16x32_bf16 v[2:5], v[196:199], v[228:231], v[2:5]
	s_setprio 0
	s_barrier
; #define PG8_STAGE(bufoff, gbase, voff) do { _Pragma("unroll") for (int _i = 0; _i < 2; ++_i) \
;         __builtin_amdgcn_global_load_lds((const unsigned*)((const char*)(gbase) + (voff)[_i]), (PG8_LAS unsigned*)(lds + (bufoff) + ldsw + _i * 8192), 16, 0, 0); } while (0)
; #define PG8_LDA(dst, b, h) do { _Pragma("unroll") for (int m = 0; m < 4; ++m) _Pragma("unroll") for (int k = 0; k < 2; ++k) dst[m][k] = *(const PG8_LAS bf16x8*)(lds + PG8_SA(b, h) + aoff + m * 2048 + k * 1024); } while (0)
; #define PG8_LDB(dst, b, h) do { _Pragma("unroll") for (int n = 0; n < 2; ++n) _Pragma("unroll") for (int k = 0; k < 2; ++k) dst[n][k] = *(const PG8_LAS bf16x8*)(lds + PG8_SB(b, h) + boff + n * 2048 + k * 1024); } while (0)
; #define PG8_MMA(ai, bj, At, Bt) do { __builtin_amdgcn_s_setprio(1); _Pragma("unroll") for (int m = 0; m < 4; ++m) _Pragma("unroll") for (int n = 0; n < 2; ++n) _Pragma("unroll") for (int k = 0; k < 2; ++k) \
;         acc[ai][bj][m][n] = __builtin_amdgcn_mfma_f32_16x16x32_bf16(Bt[n][k], At[m][k], acc[ai][bj][m][n], 0, 0, 0); __builtin_amdgcn_s_setprio(0); } while (0)
; #define PG8_WAIT_V(n) asm volatile("s_waitcnt vmcnt(" #n ")" ::: "memory")
; #define PG8_WAIT_L(n) asm volatile("s_waitcnt lgkmcnt(" #n ")" ::: "memory")
; #define PG8_BAR __builtin_amdgcn_s_barrier()
; #define PG8_SCHED __builtin_amdgcn_sched_barrier(0)
; template <class Epi, class Sched, bool ALIGN_EPI = false, bool SP2 = false>
; __device__ __forceinline__ void gemm_phase(PG8_LAS unsigned char* lds, const Gemm g, const Sched& S, const Epi& E) {
;     ...
;             PG8_LDB(B0, 1, 0); PG8_LDB(B1, 1, 1); PG8_SCHED; PG8_LDA(At, 1, 0); PG8_STAGE(PG8_SA(0, 1), a2 + hstep, voffA);
;             PG8_WAIT_V(8); PG8_WAIT_L(0); PG8_BAR; PG8_MMA(0, 0, At, B0); PG8_MMA(0, 1, At, B1); PG8_BAR; PG8_SCHED;
;             PG8_LDA(At, 1, 1); PG8_STAGE(PG8_SB(1, 0), b3, voffB); PG8_STAGE(PG8_SB(1, 1), b3 + hstep, voffB); PG8_STAGE(PG8_SA(1, 0), a3, voffA);
;             PG8_WAIT_V(8); PG8_WAIT_L(0); PG8_BAR; PG8_MMA(1, 0, At, B0); PG8_MMA(1, 1, At, B1); PG8_BAR; PG8_SCHED;
	s_add_i32 s94, 0, 0x18000
	s_add_i32 s95, 0, 0x1c000
	v_add_u32_e32 v142, s94, v181
	v_add_u32_e32 v154, s95, v181
	ds_read_b128 v[130:133], v142
	ds_read_b128 v[134:137], v142 offset:1024
	ds_read_b128 v[138:141], v142 offset:2048
	ds_read_b128 v[142:145], v142 offset:3072
	ds_read_b128 v[172:175], v154
	ds_read_b128 v[176:179], v154 offset:1024
	ds_read_b128 v[192:195], v154 offset:2048
	ds_read_b128 v[196:199], v154 offset:3072
	s_add_u32 s64, s64, 0x40000
	s_addc_u32 s65, s65, 0
	s_mov_b32 m0, s74
	ds_read_b128 v[200:203], v185 offset:32768
	ds_read_b128 v[204:207], v185 offset:33792
	ds_read_b128 v[208:211], v185 offset:34816
	ds_read_b128 v[212:215], v185 offset:35840
	ds_read_b128 v[216:219], v185 offset:36864
	ds_read_b128 v[220:223], v185 offset:37888
	ds_read_b128 v[224:227], v185 offset:38912
	ds_read_b128 v[228:231], v185 offset:39936
	global_load_lds_dwordx4 v146, s[64:65]
	s_mov_b32 m0, s75
	s_nop 0
	global_load_lds_dwordx4 v150, s[64:65]
	s_waitcnt vmcnt(24)
	s_waitcnt lgkmcnt(0)
	s_barrier
	s_setprio 1
	s_waitcnt lgkmcnt(0)
	v_mfma_f32_16x16x32_bf16 v[126:129], v[130:133], v[200:203], v[126:129]
	v_mfma_f32_16x16x32_bf16 v[122:125], v[138:141], v[200:203], v[122:125]
	v_mfma_f32_16x16x32_bf16 v[110:113], v[130:133], v[208:211], v[110:113]
	v_mfma_f32_16x16x32_bf16 v[106:109], v[138:141], v[208:211], v[106:109]
	v_mfma_f32_16x16x32_bf16 v[94:97], v[130:133], v[216:219], v[94:97]
	v_mfma_f32_16x16x32_bf16 v[90:93], v[138:141], v[216:219], v[90:93]
	v_mfma_f32_16x16x32_bf16 v[78:81], v[130:133], v[224:227], v[78:81]
	v_mfma_f32_16x16x32_bf16 v[74:77], v[138:141], v[224:227], v[74:77]
	v_mfma_f32_16x16x32_bf16 v[126:129], v[134:137], v[204:207], v[126:129]
	v_mfma_f32_16x16x32_bf16 v[122:125], v[142:145], v[204:207], v[122:125]
	v_mfma_f32_16x16x32_bf16 v[110:113], v[134:137], v[212:215], v[110:113]
	v_mfma_f32_16x16x32_bf16 v[106:109], v[142:145], v[212:215], v[106:109]
	v_mfma_f32_16x16x32_bf16 v[94:97], v[134:137], v[220:223], v[94:97]
	v_mfma_f32_16x16x32_bf16 v[90:93], v[142:145], v[220:223], v[90:93]
	v_mfma_f32_16x16x32_bf16 v[78:81], v[134:137], v[228:231], v[78:81]
	v_mfma_f32_16x16x32_bf16 v[74:77], v[142:145], v[228:231], v[74:77]
	s_setprio 0
	s_setprio 1
	v_mfma_f32_16x16x32_bf16 v[118:121], v[172:175], v[200:203], v[118:121]
	v_mfma_f32_16x16x32_bf16 v[114:117], v[192:195], v[200:203], v[114:117]
	v_mfma_f32_16x16x32_bf16 v[102:105], v[172:175], v[208:211], v[102:105]
	v_mfma_f32_16x16x32_bf16 v[98:101], v[192:195], v[208:211], v[98:101]
	v_mfma_f32_16x16x32_bf16 v[86:89], v[172:175], v[216:219], v[86:89]
	v_mfma_f32_16x16x32_bf16 v[82:85], v[192:195], v[216:219], v[82:85]
	v_mfma_f32_16x16x32_bf16 v[70:73], v[172:175], v[224:227], v[70:73]
	v_mfma_f32_16x16x32_bf16 v[66:69], v[192:195], v[224:227], v[66:69]
	v_mfma_f32_16x16x32_bf16 v[118:121], v[176:179], v[204:207], v[118:121]
	v_mfma_f32_16x16x32_bf16 v[114:117], v[196:199], v[204:207], v[114:117]
	v_mfma_f32_16x16x32_bf16 v[102:105], v[176:179], v[212:215], v[102:105]
	v_mfma_f32_16x16x32_bf16 v[98:101], v[196:199], v[212:215], v[98:101]
	v_mfma_f32_16x16x32_bf16 v[86:89], v[176:179], v[220:223], v[86:89]
	v_mfma_f32_16x16x32_bf16 v[82:85], v[196:199], v[220:223], v[82:85]
	v_mfma_f32_16x16x32_bf16 v[70:73], v[176:179], v[228:231], v[70:73]
	v_mfma_f32_16x16x32_bf16 v[66:69], v[196:199], v[228:231], v[66:69]
	s_setprio 0
	s_barrier
	s_add_i32 s96, s94, s72
	s_add_u32 s12, s50, 0x80
	s_addc_u32 s13, s51, 0
	s_mov_b32 m0, s96
	ds_read_b128 v[200:203], v185 offset:49152
	ds_read_b128 v[204:207], v185 offset:50176
	ds_read_b128 v[208:211], v185 offset:51200
	ds_read_b128 v[212:215], v185 offset:52224
	ds_read_b128 v[216:219], v185 offset:53248
	ds_read_b128 v[220:223], v185 offset:54272
	ds_read_b128 v[224:227], v185 offset:55296
	ds_read_b128 v[228:231], v185 offset:56320
	global_load_lds_dwordx4 v148, s[12:13]
	s_add_i32 m0, s96, 0x2000
	s_add_u32 s50, s50, 0x40080
	s_addc_u32 s51, s51, 0
	s_add_i32 s96, s95, s72
	global_load_lds_dwordx4 v152, s[12:13]
	s_mov_b32 m0, s96
	s_nop 0
	global_load_lds_dwordx4 v148, s[50:51]
	s_add_i32 m0, s96, 0x2000
	s_nop 0
	global_load_lds_dwordx4 v152, s[50:51]
	s_add_u32 s64, s64, 0xfffc0080
	s_addc_u32 s65, s65, -1
	s_mov_b32 m0, s82
	s_nop 0
	global_load_lds_dwordx4 v146, s[64:65]
	s_mov_b32 m0, s83
	s_nop 0
	global_load_lds_dwordx4 v150, s[64:65]
	s_waitcnt vmcnt(8)
	s_waitcnt lgkmcnt(0)
	s_barrier
	s_setprio 1
	s_waitcnt lgkmcnt(0)
	v_mfma_f32_16x16x32_bf16 v[62:65], v[130:133], v[200:203], v[62:65]
	v_mfma_f32_16x16x32_bf16 v[58:61], v[138:141], v[200:203], v[58:61]
	v_mfma_f32_16x16x32_bf16 v[46:49], v[130:133], v[208:211], v[46:49]
	v_mfma_f32_16x16x32_bf16 v[42:45], v[138:141], v[208:211], v[42:45]
	v_mfma_f32_16x16x32_bf16 v[30:33], v[130:133], v[216:219], v[30:33]
	v_mfma_f32_16x16x32_bf16 v[26:29], v[138:141], v[216:219], v[26:29]
	v_mfma_f32_16x16x32_bf16 v[14:17], v[130:133], v[224:227], v[14:17]
	v_mfma_f32_16x16x32_bf16 v[10:13], v[138:141], v[224:227], v[10:13]
	v_mfma_f32_16x16x32_bf16 v[62:65], v[134:137], v[204:207], v[62:65]
	v_mfma_f32_16x16x32_bf16 v[58:61], v[142:145], v[204:207], v[58:61]
	v_mfma_f32_16x16x32_bf16 v[46:49], v[134:137], v[212:215], v[46:49]
	v_mfma_f32_16x16x32_bf16 v[42:45], v[142:145], v[212:215], v[42:45]
	v_mfma_f32_16x16x32_bf16 v[30:33], v[134:137], v[220:223], v[30:33]
	v_mfma_f32_16x16x32_bf16 v[26:29], v[142:145], v[220:223], v[26:29]
	v_mfma_f32_16x16x32_bf16 v[14:17], v[134:137], v[228:231], v[14:17]
	v_mfma_f32_16x16x32_bf16 v[10:13], v[142:145], v[228:231], v[10:13]
	s_setprio 0
	s_setprio 1
	v_mfma_f32_16x16x32_bf16 v[54:57], v[172:175], v[200:203], v[54:57]
	v_mfma_f32_16x16x32_bf16 v[50:53], v[192:195], v[200:203], v[50:53]
	v_mfma_f32_16x16x32_bf16 v[38:41], v[172:175], v[208:211], v[38:41]
	v_mfma_f32_16x16x32_bf16 v[34:37], v[192:195], v[208:211], v[34:37]
	v_mfma_f32_16x16x32_bf16 v[22:25], v[172:175], v[216:219], v[22:25]
	v_mfma_f32_16x16x32_bf16 v[18:21], v[192:195], v[216:219], v[18:21]
	v_mfma_f32_16x16x32_bf16 v[6:9], v[172:175], v[224:227], v[6:9]
	v_mfma_f32_16x16x32_bf16 v[2:5], v[192:195], v[224:227], v[2:5]
	v_mfma_f32_16x16x32_bf16 v[54:57], v[176:179], v[204:207], v[54:57]
	v_mfma_f32_16x16x32_bf16 v[50:53], v[196:199], v[204:207], v[50:53]
	v_mfma_f32_16x16x32_bf16 v[38:41], v[176:179], v[212:215], v[38:41]
	v_mfma_f32_16x16x32_bf16 v[34:37], v[196:199], v[212:215], v[34:37]
	v_mfma_f32_16x16x32_bf16 v[22:25], v[176:179], v[220:223], v[22:25]
	v_mfma_f32_16x16x32_bf16 v[18:21], v[196:199], v[220:223], v[18:21]
	v_mfma_f32_16x16x32_bf16 v[6:9], v[176:179], v[228:231], v[6:9]
	v_mfma_f32_16x16x32_bf16 v[2:5], v[196:199], v[228:231], v[2:5]
	s_setprio 0
	s_barrier
	s_add_i32 s93, s93, 2
	s_add_u32 s48, s48, 0x100
	s_addc_u32 s49, s49, 0
	s_add_u32 s41, s41, 0x100
	s_addc_u32 s92, s92, 0
	s_branch .LBB0_162
